# P0 rebalanced split plus counted vmcnt waits in the conversion loops (conversion-only workgroups now on the critical path)
# speedup vs baseline: 1.0084x; 1.0023x over previous
.Lcv1_w1_go:
	ds_write_b128 v149, v[6:9]
	ds_write_b128 v150, v[2:5] offset:8448
	ds_write_b128 v151, v[14:17] offset:16896
	ds_write_b128 v152, v[10:13] offset:25344
	s_cbranch_vccnz .LBB0_190
	s_sub_i32 s20, s42, 64
	s_add_i32 s21, s43, 0xffffe7c0
	s_cmp_lt_u32 s44, 33
	s_cselect_b32 s23, s20, s21
	s_cmpk_lt_i32 s23, 0xe80
	s_cselect_b32 s20, 0, 0x200
	s_add_i32 s22, s20, s23
	s_cmpk_lt_u32 s22, 0x1640
	s_cselect_b32 s20, 2, 3
	s_cmpk_gt_u32 s22, 0x107f
	s_cselect_b32 s46, s20, 1
	s_cmpk_gt_i32 s22, 0xaff
	s_cselect_b64 s[20:21], -1, 0
	s_and_b64 s[20:21], s[20:21], exec
	s_cselect_b32 s45, s46, 0
	s_cmp_eq_u32 s45, 2
	s_cselect_b64 s[26:27], -1, 0
	s_and_b64 s[20:21], s[26:27], exec
	s_cselect_b32 s24, s36, 0xffffe9c0
	s_cselect_b32 s25, 46, 16
	s_cmpk_gt_i32 s22, 0xaff
	s_cselect_b64 s[20:21], -1, 0
	s_and_b64 s[20:21], s[20:21], exec
	s_cselect_b32 s25, s25, 0x58
	s_add_i32 s20, s22, 0xfffff500
	s_cmpk_lt_u32 s20, 0x580
	s_cselect_b64 s[28:29], -1, 0
	s_and_b64 s[20:21], s[28:29], exec
	s_cselect_b32 s24, 0xfffff500, s24
	s_cmpk_gt_i32 s22, 0xaff
	s_cselect_b64 s[20:21], -1, 0
	s_and_b64 vcc, s[20:21], exec
	s_cselect_b32 s20, s24, 0
	s_abs_i32 s21, s25
	v_cvt_f32_u32_e32 v2, s21
	s_sub_i32 s47, 0, s21
	s_add_i32 s20, s20, s22
	s_ashr_i32 s20, s20, 2
	v_rcp_iflag_f32_e32 v2, v2
	s_abs_i32 s24, s20
	s_xor_b32 s22, s20, s25
	s_ashr_i32 s22, s22, 31
	v_mul_f32_e32 v2, 0x4f7ffffe, v2
	v_cvt_u32_f32_e32 v2, v2
	s_nop 0
	v_readfirstlane_b32 s48, v2
	s_mul_i32 s47, s47, s48
	s_mul_hi_u32 s47, s48, s47
	s_add_i32 s48, s48, s47
	s_mul_hi_u32 s47, s24, s48
	s_mul_i32 s48, s47, s21
	s_sub_i32 s24, s24, s48
	s_add_i32 s48, s47, 1
	s_sub_i32 s49, s24, s21
	s_cmp_ge_u32 s24, s21
	s_cselect_b32 s47, s48, s47
	s_cselect_b32 s24, s49, s24
	s_add_i32 s48, s47, 1
	s_cmp_ge_u32 s24, s21
	s_cselect_b32 s21, s48, s47
	s_xor_b32 s21, s21, s22
	s_sub_i32 s47, s21, s22
	s_mul_i32 s21, s47, s25
	s_sub_i32 s48, s20, s21
	s_mov_b64 s[24:25], -1
	s_cbranch_vccnz .LBB0_179
	s_lshl_b32 s21, s48, 6
	s_and_b32 s21, s21, 0xffffff80
	s_and_b32 s20, s48, 1
	s_add_i32 s22, s21, 0x1600
	s_cmp_eq_u32 s20, 0
	s_cselect_b32 s22, s21, s22
	s_mov_b64 s[24:25], 0
	s_waitcnt lgkmcnt(0)
	s_mov_b64 s[20:21], s[10:11]

.LBB0_190:
	s_add_i32 s20, s42, 0xffffff40
	s_add_i32 s21, s43, 0xffffe5c0
	s_cmp_lt_u32 s44, 35
	s_cselect_b32 s28, s20, s21
	s_cmpk_lt_i32 s28, 0xe80
	s_cselect_b32 s20, 0, 0x200
	s_add_i32 s29, s20, s28
	s_cmpk_gt_i32 s29, 0xaff
	s_cselect_b64 s[20:21], -1, 0
	s_add_i32 s22, s29, 0xfffff500
	s_cmpk_lt_u32 s22, 0x580
	s_cselect_b64 s[22:23], -1, 0
	s_add_i32 s24, s29, 0xffffef80
	s_cmpk_lt_u32 s24, 0x5c0
	s_cselect_b64 s[24:25], -1, 0
	s_and_b64 s[26:27], s[24:25], exec
	s_cselect_b32 s45, s36, 0xffffe9c0
	s_and_b64 s[26:27], s[22:23], exec
	s_cselect_b32 s45, 0xfffff500, s45
	s_and_b64 s[26:27], s[20:21], exec
	s_cselect_b32 s26, s45, 0
	s_add_i32 s29, s26, s29
	s_and_b64 s[26:27], s[24:25], exec
	s_cselect_b32 s45, 46, 16
	s_and_b64 s[26:27], s[20:21], exec
	s_cselect_b32 s26, s45, 0x58
	s_abs_i32 s27, s26
	v_cvt_f32_u32_e32 v37, s27
	s_sub_i32 s47, 0, s27
	s_ashr_i32 s29, s29, 2
	s_abs_i32 s46, s29
	v_rcp_iflag_f32_e32 v37, v37
	s_ashr_i32 s45, s29, 31
	v_add_u32_e32 v38, 0x400, v154
	v_add_u32_e32 v39, 0x800, v154
	v_mul_f32_e32 v37, 0x4f7ffffe, v37
	v_cvt_u32_f32_e32 v37, v37
	v_add_u32_e32 v41, 0x1000, v154
	s_waitcnt lgkmcnt(0)
	s_barrier
	v_readfirstlane_b32 s48, v37
	s_mul_i32 s47, s47, s48
	s_mul_hi_u32 s47, s48, s47
	s_add_i32 s48, s48, s47
	s_mul_hi_u32 s47, s46, s48
	s_mul_i32 s48, s47, s27
	s_sub_i32 s46, s46, s48
	s_add_i32 s48, s47, 1
	s_sub_i32 s49, s46, s27
	s_cmp_ge_u32 s46, s27
	s_cselect_b32 s47, s48, s47
	s_cselect_b32 s46, s49, s46
	s_add_i32 s48, s47, 1
	s_cmp_ge_u32 s46, s27
	s_cselect_b32 s27, s48, s47
	s_xor_b32 s27, s27, s45
	s_sub_i32 s27, s27, s45
	s_mul_i32 s26, s27, s26
	s_sub_i32 s26, s29, s26
	s_and_b64 s[24:25], s[24:25], exec
	s_cselect_b32 s29, s39, 0x5900000
	s_and_b64 s[24:25], s[22:23], exec
	s_cselect_b32 s24, 0x2c00000, s29
	s_and_b64 s[20:21], s[20:21], exec
	s_cselect_b32 s21, s24, 0
	s_lshl_b32 s24, s28, 6
	ds_read2_b32 v[46:47], v154 offset1:132
	ds_read2_b32 v[48:49], v38 offset0:8 offset1:140
	ds_read2_b32 v[50:51], v39 offset0:16 offset1:148
	ds_read2_b32 v[54:55], v41 offset0:32 offset1:164
	s_lshl_b32 s20, s27, 8
	s_and_b32 s24, s24, 0xc0
	s_or_b32 s20, s20, s24
	v_add_u32_e32 v40, 0xc00, v154
	s_and_b64 s[22:23], s[22:23], exec
	ds_read2_b32 v[52:53], v40 offset0:24 offset1:156
	v_add_u32_e32 v42, 0x1400, v154
	v_add_u32_e32 v43, 0x1800, v154
	v_add_u32_e32 v44, 0x1c00, v154
	s_cselect_b32 s24, 0x1600, s37
	s_add_u32 s22, s14, s21
	ds_read2_b32 v[56:57], v42 offset0:40 offset1:172
	ds_read2_b32 v[58:59], v43 offset0:48 offset1:180
	ds_read2_b32 v[60:61], v44 offset0:56 offset1:188
	v_lshl_add_u32 v37, s26, 7, v153
	s_addc_u32 s23, s15, 0
	s_waitcnt lgkmcnt(7)
	v_cvt_pk_bf16_f32 v46, v46, v47
	s_waitcnt lgkmcnt(6)
	v_cvt_pk_bf16_f32 v47, v48, v49
	s_waitcnt lgkmcnt(5)
	v_cvt_pk_bf16_f32 v48, v50, v51
	s_waitcnt lgkmcnt(4)
	v_cvt_pk_bf16_f32 v50, v54, v55
	v_mad_i64_i32 v[54:55], s[24:25], s24, v37, 0
	v_lshl_add_u64 v[54:55], v[54:55], 1, s[22:23]
	s_ashr_i32 s21, s20, 31
	v_lshl_add_u64 v[54:55], s[20:21], 1, v[54:55]
	s_add_i32 s45, s44, 1
	s_waitcnt lgkmcnt(3)
	v_cvt_pk_bf16_f32 v49, v52, v53
	v_lshl_add_u64 v[54:55], v[54:55], 0, v[34:35]
	s_cmp_ge_i32 s45, s34
	s_waitcnt lgkmcnt(2)
	v_cvt_pk_bf16_f32 v51, v56, v57
	s_waitcnt lgkmcnt(1)
	v_cvt_pk_bf16_f32 v52, v58, v59
	s_waitcnt lgkmcnt(0)
	v_cvt_pk_bf16_f32 v53, v60, v61
	global_store_dwordx4 v[54:55], v[46:49], off
	global_store_dwordx4 v[54:55], v[50:53], off offset:16
	s_barrier
	s_cbranch_scc1 .LBB0_175
	s_cmp_ge_i32 s41, s34
	s_cbranch_scc1 .Lcv1_w2_drain
	s_cmp_eq_u32 s44, 0
	s_cbranch_scc1 .Lcv1_w2_first
	s_waitcnt vmcnt(8)
	s_branch .Lcv1_w2_go

.Lcv1_w2_go:
	s_add_i32 s20, s44, 3
	s_cmp_ge_i32 s20, s34
	ds_write_b128 v149, v[18:21]
	ds_write_b128 v150, v[22:25] offset:8448
	ds_write_b128 v151, v[26:29] offset:16896
	ds_write_b128 v152, v[30:33] offset:25344
	s_cbranch_scc1 .LBB0_174
	s_add_i32 s20, s43, 0xffffe8c0
	s_cmp_lt_u32 s44, 32
	s_cselect_b32 s23, s42, s20
	s_cmpk_lt_i32 s23, 0xe80
	s_cselect_b32 s20, 0, 0x200
	s_add_i32 s22, s20, s23
	s_cmpk_lt_u32 s22, 0x1640
	s_cselect_b32 s20, 2, 3
	s_cmpk_gt_u32 s22, 0x107f
	s_cselect_b32 s46, s20, 1
	s_cmpk_gt_i32 s22, 0xaff
	s_cselect_b64 s[20:21], -1, 0
	s_and_b64 s[20:21], s[20:21], exec
	s_cselect_b32 s44, s46, 0
	s_cmp_eq_u32 s44, 2
	s_cselect_b64 s[26:27], -1, 0
	s_and_b64 s[20:21], s[26:27], exec
	s_cselect_b32 s24, s36, 0xffffe9c0
	s_cselect_b32 s25, 46, 16
	s_cmpk_gt_i32 s22, 0xaff
	s_cselect_b64 s[20:21], -1, 0
	s_and_b64 s[20:21], s[20:21], exec
	s_cselect_b32 s25, s25, 0x58
	s_add_i32 s20, s22, 0xfffff500
	s_cmpk_lt_u32 s20, 0x580
	s_cselect_b64 s[28:29], -1, 0
	s_and_b64 s[20:21], s[28:29], exec
	s_cselect_b32 s24, 0xfffff500, s24
	s_cmpk_gt_i32 s22, 0xaff
	s_cselect_b64 s[20:21], -1, 0
	s_and_b64 vcc, s[20:21], exec
	s_cselect_b32 s20, s24, 0
	s_abs_i32 s21, s25
	v_cvt_f32_u32_e32 v18, s21
	s_sub_i32 s47, 0, s21
	s_add_i32 s20, s20, s22
	s_ashr_i32 s20, s20, 2
	v_rcp_iflag_f32_e32 v18, v18
	s_abs_i32 s24, s20
	s_xor_b32 s22, s20, s25
	s_ashr_i32 s22, s22, 31
	v_mul_f32_e32 v18, 0x4f7ffffe, v18
	v_cvt_u32_f32_e32 v18, v18
	s_nop 0
	v_readfirstlane_b32 s48, v18
	s_mul_i32 s47, s47, s48
	s_mul_hi_u32 s47, s48, s47
	s_add_i32 s48, s48, s47
	s_mul_hi_u32 s47, s24, s48
	s_mul_i32 s48, s47, s21
	s_sub_i32 s24, s24, s48
	s_add_i32 s48, s47, 1
	s_sub_i32 s49, s24, s21
	s_cmp_ge_u32 s24, s21
	s_cselect_b32 s47, s48, s47
	s_cselect_b32 s24, s49, s24
	s_add_i32 s48, s47, 1
	s_cmp_ge_u32 s24, s21
	s_cselect_b32 s21, s48, s47
	s_xor_b32 s21, s21, s22
	s_sub_i32 s47, s21, s22
	s_mul_i32 s21, s47, s25
	s_sub_i32 s48, s20, s21
	s_mov_b64 s[24:25], -1
	s_cbranch_vccnz .LBB0_194
	s_lshl_b32 s21, s48, 6
	s_and_b32 s21, s21, 0xffffff80
	s_and_b32 s20, s48, 1
	s_add_i32 s22, s21, 0x1600
	s_cmp_eq_u32 s20, 0
	s_cselect_b32 s22, s21, s22
	s_mov_b64 s[24:25], 0
	s_mov_b64 s[20:21], s[10:11]
